# G3 tile-tail rebalancing: last 256 rows (16 tiles, formerly a 3rd round on 16 blocks) split into 512 16x32 pieces, K split over 4 waves + LDS reduce
# speedup vs baseline: 1.0033x; 1.0033x over previous
; __device__ __forceinline__ int otid() { int t = threadIdx.x; asm volatile("" : "+v"(t)); return t; }
; __device__ __forceinline__ int tile_iters(int MT, int NTn) {
;   const int G = gridDim.x;
;   const int nx = (G % 8 == 0) ? 8 : 1;
;   const int nloc = G / nx;
;   const int nchunks = (MT * NTn + nloc - 1) / nloc;
;   return (nchunks + nx - 1) / nx;
; }
; __device__ __forceinline__ void phase_gemm_out(const Params& p, char* smem) {
;     ...
;   const int tid_ = otid(); const int lane = tid_ & 63, wave = tid_ >> 6, wm = wave >> 1, wn = wave & 1;
;   const int MT = NT / 128, NTn = 8;
;   const int iters = tile_iters(MT, NTn);
;   for (int it = 0; it < iters; ++it) {
;     int mt, nt;
;     if (!tile_at(it, MT, NTn, mt, nt)) break;
.LBB0_717:
	s_nop 0
	v_readlane_b32 s0, v241, 25
	v_readlane_b32 s1, v241, 26
	s_and_b64 vcc, exec, s[0:1]
	s_cbranch_vccz .LBB0_728
	v_readlane_b32 s12, v244, 9
	v_mov_b32_e32 v0, v178
	v_readlane_b32 s13, v244, 10
	s_load_dword s16, s[12:13], 0x0
	s_waitcnt lgkmcnt(0)
	s_and_b32 s12, s16, 7
	s_cmp_eq_u32 s12, 0
	s_cselect_b64 s[12:13], -1, 0
	s_and_b64 s[14:15], s[12:13], exec
	s_cselect_b32 s15, 8, 1
	v_cvt_f32_ubyte0_e32 v1, s15
	v_rcp_iflag_f32_e32 v1, v1
	s_sub_i32 s17, 0, s15
	s_ashr_i32 s14, s16, 31
	s_abs_i32 s16, s16
	v_mul_f32_e32 v1, 0x4f7ffffe, v1
	v_cvt_u32_f32_e32 v1, v1
	s_nop 0
	v_readfirstlane_b32 s18, v1
	s_mul_i32 s17, s17, s18
	s_mul_hi_u32 s17, s18, s17
	s_add_i32 s18, s18, s17
	s_mul_hi_u32 s17, s16, s18
	s_mul_i32 s22, s17, s15
	s_sub_i32 s16, s16, s22
	s_add_i32 s23, s17, 1
	s_sub_i32 s22, s16, s15
	s_cmp_ge_u32 s16, s15
	s_cselect_b32 s17, s23, s17
	s_cselect_b32 s16, s22, s16
	s_add_i32 s22, s17, 1
	s_cmp_ge_u32 s16, s15
	s_cselect_b32 s16, s22, s17
	s_xor_b32 s16, s16, s14
	s_sub_i32 s22, s16, s14
	s_abs_i32 s14, s22
	v_cvt_f32_u32_e32 v1, s14
	s_add_i32 s16, s22, 0x3ff
	s_sub_i32 s17, 0xfffffc01, s22
	s_xor_b32 s23, s16, s22
	v_rcp_iflag_f32_e32 v1, v1
	s_max_i32 s16, s16, s17
	s_sub_i32 s17, 0, s14
	s_ashr_i32 s23, s23, 31
	v_mul_f32_e32 v1, 0x4f7ffffe, v1
	v_cvt_u32_f32_e32 v1, v1
	s_nop 0
	v_readfirstlane_b32 s24, v1
	s_mul_i32 s17, s17, s24
	s_mul_hi_u32 s17, s24, s17
	s_add_i32 s24, s24, s17
	s_mul_hi_u32 s17, s16, s24
	s_mul_i32 s24, s17, s14
	s_sub_i32 s16, s16, s24
	s_add_i32 s25, s17, 1
	s_sub_i32 s24, s16, s14
	s_cmp_ge_u32 s16, s14
	s_cselect_b32 s17, s25, s17
	s_cselect_b32 s16, s24, s16
	s_add_i32 s24, s17, 1
	s_cmp_ge_u32 s16, s14
	s_cselect_b32 s16, s24, s17
	s_xor_b32 s16, s16, s23
	s_add_i32 s14, s15, -1
	s_sub_i32 s16, s16, s23
	s_add_i32 s16, s14, s16
	s_ashr_i32 s17, s16, 31
	s_abs_i32 s16, s16
	s_mul_hi_u32 s18, s16, s18
	s_mul_i32 s23, s18, s15
	s_sub_i32 s16, s16, s23
	s_add_i32 s24, s18, 1
	s_sub_i32 s23, s16, s15
	s_cmp_ge_u32 s16, s15
	s_cselect_b32 s18, s24, s18
	s_cselect_b32 s16, s23, s16
	s_add_i32 s23, s18, 1
	s_cmp_ge_u32 s16, s15
	s_cselect_b32 s15, s23, s18
	s_xor_b32 s15, s15, s17
	s_sub_i32 s23, s15, s17
	s_cmp_lt_i32 s23, 1
	s_cbranch_scc1 .LBB0_727
	v_readlane_b32 s15, v244, 0
	s_and_b32 s24, s14, s15
	v_ashrrev_i32_e32 v1, 1, v0
	v_and_b32_e32 v2, 15, v0
	s_movk_i32 s0, 0xffc0
	s_and_b64 s[12:13], s[12:13], exec
	v_and_or_b32 v134, v1, s0, v2
	v_lshrrev_b32_e32 v1, 2, v0
	s_cselect_b32 s26, 3, 0
	v_and_b32_e32 v1, 12, v1
	s_mov_b32 s25, 0
	s_lshr_b32 s27, s15, s26
	v_and_or_b32 v135, v0, 64, v1
	s_branch .LBB0_722

; #define GLOAD(RA, RB, kt_)                                                         \
;   _Pragma("unroll") for (int i = 0; i < 4; ++i) {                                  \
;     RA[i] = *(const u32x4*)(ap + (size_t)(32 * i) * lda + ((kt_) << 6));           \
;     RB[i] = *(const u32x4*)(bp + (size_t)(32 * i) * ldb + ((kt_) << 6));           \
;   }
; #define SWRITE(RA, RB, buf_)                                                       \
;   _Pragma("unroll") for (int i = 0; i < 4; ++i) {                                  \
;     *(u32x4*)(wA + (buf_) * BUF + 32 * i * LDS_STRIDE) = RA[i];                    \
;     *(u32x4*)(wB + (buf_) * BUF + 32 * i * LDS_STRIDE) = RB[i];                    \
;   }
; __device__ __forceinline__ bool tile_at(int it, int MT, int NTn, int& mt, int& nt) {
;   const int G = gridDim.x;
;   const int nx = (G % 8 == 0) ? 8 : 1;
;   const int x = blockIdx.x % nx, j = blockIdx.x / nx, nloc = G / nx;
;   const int ch = x + nx * it;
;   const int q = ch * nloc + j;
;   if (q >= MT * NTn) return false;
;   const int gs = 8 * NTn;
;   const int g = q / gs, rem = q - g * gs;
;   const int gsz = min(8, MT - g * 8);
;   nt = rem / gsz;
;   mt = g * 8 + (rem - nt * gsz);
;   return true;
; }
; template <bool DEEP>
; __device__ __forceinline__ void gemm_core(const bf16_t* __restrict__ A, int lda, const bf16_t* __restrict__ Bt, int ldb,
;                                           int K, f32x4 (&acc)[4][4], char* smem) {
;     ...
;   u32x4 ra0[4], rb0[4];
;   GLOAD(ra0, rb0, 0);
;   if (DEEP) {
;     u32x4 ra1[4], rb1[4];
;     GLOAD(ra1, rb1, 1);
;     __syncthreads();
;     SWRITE(ra0, rb0, 0);
;     __syncthreads();
.LBB0_722:
	s_lshl_b32 s12, s25, s26
	s_add_i32 s12, s12, s24
	s_mul_i32 s14, s12, s22
	s_add_i32 s14, s14, s27
	s_cmpk_gt_i32 s14, 0x3ff
	s_mov_b64 s[12:13], -1
	s_cbranch_scc1 .LBB0_721
	s_ashr_i32 s12, s14, 31
	s_lshr_b32 s12, s12, 26
	s_add_i32 s12, s14, s12
	s_ashr_i32 s13, s12, 6
	s_lshl_b32 s13, s13, 3
	s_sub_i32 s15, 0x82, s13
	s_min_u32 s15, s15, 8
	v_cvt_f32_ubyte0_e32 v0, s15
	v_rcp_iflag_f32_e32 v0, v0
	s_sub_i32 s17, 0, s15
	s_andn2_b32 s12, s12, 63
	s_sub_i32 s14, s14, s12
	v_mul_f32_e32 v0, 0x4f7ffffe, v0
	v_cvt_u32_f32_e32 v0, v0
	s_abs_i32 s16, s14
	s_ashr_i32 s12, s14, 31
	s_waitcnt vmcnt(4)
	v_mov_b32_e32 v34, v178
	v_readfirstlane_b32 s18, v0
	s_mul_i32 s17, s17, s18
	s_mul_hi_u32 s17, s18, s17
	s_add_i32 s18, s18, s17
	s_mul_hi_u32 s17, s16, s18
	s_mul_i32 s18, s17, s15
	s_sub_i32 s16, s16, s18
	s_add_i32 s28, s17, 1
	s_sub_i32 s18, s16, s15
	s_cmp_ge_u32 s16, s15
	s_cselect_b32 s17, s28, s17
	s_cselect_b32 s16, s18, s16
	s_add_i32 s18, s17, 1
	s_cmp_ge_u32 s16, s15
	s_cselect_b32 s16, s18, s17
	s_xor_b32 s16, s16, s12
	s_sub_i32 s12, s16, s12
	s_add_i32 s14, s14, s13
	s_mul_i32 s13, s12, s15
	s_sub_i32 s14, s14, s13
	s_ashr_i32 s15, s14, 31
	s_lshl_b64 s[16:17], s[14:15], 18
	v_readlane_b32 s28, v244, 7
	v_readlane_b32 s29, v244, 8
	s_add_u32 s16, s28, s16
	s_addc_u32 s17, s29, s17
	v_ashrrev_i32_e32 v32, 3, v34
	s_ashr_i32 s13, s12, 31
	v_ashrrev_i32_e32 v33, 31, v32
	s_lshl_b64 s[28:29], s[12:13], 18
	v_readlane_b32 s0, v243, 48
	v_lshlrev_b64 v[4:5], 11, v[32:33]
	v_lshlrev_b32_e32 v2, 4, v34
	s_add_u32 s28, s0, s28
	v_readlane_b32 s0, v243, 49
	v_lshl_add_u64 v[0:1], s[16:17], 0, v[4:5]
	v_and_b32_e32 v2, 0x70, v2
	s_addc_u32 s29, s0, s29
	v_lshl_add_u64 v[0:1], v[0:1], 0, v[2:3]
	s_mov_b32 s0, 0x10000
	v_lshl_add_u64 v[4:5], s[28:29], 0, v[4:5]
	v_add_co_u32_e32 v40, vcc, s0, v0
	v_lshl_add_u64 v[132:133], v[4:5], 0, v[2:3]
	s_nop 0
	v_addc_co_u32_e32 v41, vcc, 0, v1, vcc
	v_add_co_u32_e32 v48, vcc, s0, v132
	s_mov_b32 s0, 0x20000
	s_nop 0
	v_addc_co_u32_e32 v49, vcc, 0, v133, vcc
	v_add_co_u32_e32 v42, vcc, s0, v0
	v_and_b32_e32 v2, 15, v34
	s_nop 0
	v_addc_co_u32_e32 v43, vcc, 0, v1, vcc
	v_add_co_u32_e32 v56, vcc, s0, v132
	s_mov_b32 s0, 0x30000
	s_nop 0
	v_addc_co_u32_e32 v57, vcc, 0, v133, vcc
	v_add_co_u32_e32 v50, vcc, s0, v0
	v_lshrrev_b32_e32 v33, 4, v34
	v_lshrrev_b32_e32 v44, 1, v34
	v_bfe_u32 v45, v34, 1, 3
	v_addc_co_u32_e32 v51, vcc, 0, v1, vcc
	v_bitop3_b32 v62, v33, v45, 3 bitop3:0x6c
	v_and_or_b32 v2, v44, s79, v2
	v_xor_b32_e32 v33, v33, v34
	v_add_co_u32_e32 v60, vcc, s0, v132
	v_lshlrev_b32_e32 v73, 7, v2
	v_lshlrev_b32_e32 v2, 4, v33
	v_addc_co_u32_e32 v61, vcc, 0, v133, vcc
	v_bfe_u32 v35, v34, 4, 2
	v_lshlrev_b32_e32 v46, 7, v34
	v_and_b32_e32 v2, 0x70, v2
	global_load_dwordx4 v[4:7], v[0:1], off
	global_load_dwordx4 v[8:11], v[132:133], off
	global_load_dwordx4 v[12:15], v[40:41], off
	global_load_dwordx4 v[20:23], v[42:43], off
	global_load_dwordx4 v[16:19], v[48:49], off
	global_load_dwordx4 v[28:31], v[50:51], off
	global_load_dwordx4 v[24:27], v[56:57], off
	global_load_dwordx4 v[36:39], v[60:61], off
	v_bitop3_b32 v63, v35, v45, 4 bitop3:0x36
	v_and_b32_e32 v72, 0x2780, v46
	v_lshl_or_b32 v2, v32, 7, v2
	global_load_dwordx4 v[32:35], v[0:1], off offset:128
	global_load_dwordx4 v[44:47], v[40:41], off offset:128
	global_load_dwordx4 v[52:55], v[42:43], off offset:128
	global_load_dwordx4 v[64:67], v[50:51], off offset:128
	s_nop 0
	global_load_dwordx4 v[40:43], v[132:133], off offset:128
	s_nop 0
	global_load_dwordx4 v[48:51], v[48:49], off offset:128
	s_nop 0
	global_load_dwordx4 v[56:59], v[56:57], off offset:128
	s_nop 0
	global_load_dwordx4 v[68:71], v[60:61], off offset:128
	s_barrier
	s_mov_b32 s13, 0
	s_waitcnt vmcnt(15)
	ds_write_b128 v2, v[4:7]
	s_waitcnt vmcnt(13)
	ds_write_b128 v2, v[12:15] offset:4096
	s_waitcnt vmcnt(12)
	ds_write_b128 v2, v[20:23] offset:8192
	s_waitcnt vmcnt(10)
	ds_write_b128 v2, v[28:31] offset:12288
	ds_write_b128 v2, v[8:11] offset:32768
	ds_write_b128 v2, v[16:19] offset:36864
	s_waitcnt vmcnt(9)
	ds_write_b128 v2, v[24:27] offset:40960
	s_waitcnt vmcnt(8)
	ds_write_b128 v2, v[36:39] offset:45056
	v_lshlrev_b32_e32 v4, 4, v62
	v_or_b32_e32 v136, v73, v4
	v_or_b32_e32 v137, v72, v4
	v_lshlrev_b32_e32 v4, 4, v63
	v_or_b32_e32 v138, v73, v4
	v_or_b32_e32 v139, v72, v4
	v_mov_b32_e32 v4, 0
	v_mov_b32_e32 v5, v4
	v_mov_b32_e32 v6, v4
	v_mov_b32_e32 v7, v4
	v_mov_b32_e32 v8, v4
	v_mov_b32_e32 v9, v4
	v_mov_b32_e32 v10, v4
	v_mov_b32_e32 v11, v4
	v_mov_b32_e32 v12, v4
	v_mov_b32_e32 v13, v4
	v_mov_b32_e32 v14, v4
	v_mov_b32_e32 v15, v4
	v_mov_b32_e32 v16, v4
	v_mov_b32_e32 v17, v4
	v_mov_b32_e32 v18, v4
	v_mov_b32_e32 v19, v4
	v_mov_b32_e32 v20, v4
	v_mov_b32_e32 v21, v4
	v_mov_b32_e32 v22, v4
	v_mov_b32_e32 v23, v4
	v_mov_b32_e32 v24, v4
	v_mov_b32_e32 v25, v4
	v_mov_b32_e32 v26, v4
	v_mov_b32_e32 v27, v4
	v_mov_b32_e32 v28, v4
	v_mov_b32_e32 v29, v4
	v_mov_b32_e32 v30, v4
	v_mov_b32_e32 v31, v4
	v_mov_b32_e32 v36, v4
	v_mov_b32_e32 v37, v4
	v_mov_b32_e32 v38, v4
	v_mov_b32_e32 v39, v4
	v_mov_b32_e32 v60, v4
	v_mov_b32_e32 v61, v4
	v_mov_b32_e32 v62, v4
	v_mov_b32_e32 v63, v4
	v_mov_b32_e32 v72, v4
	v_mov_b32_e32 v73, v4
	v_mov_b32_e32 v74, v4
	v_mov_b32_e32 v75, v4
	v_mov_b32_e32 v76, v4
	v_mov_b32_e32 v77, v4
	v_mov_b32_e32 v78, v4
	v_mov_b32_e32 v79, v4
	v_mov_b32_e32 v80, v4
	v_mov_b32_e32 v81, v4
	v_mov_b32_e32 v82, v4
	v_mov_b32_e32 v83, v4
	v_mov_b32_e32 v84, v4
	v_mov_b32_e32 v85, v4
	v_mov_b32_e32 v86, v4
	v_mov_b32_e32 v87, v4
	v_mov_b32_e32 v88, v4
	v_mov_b32_e32 v89, v4
	v_mov_b32_e32 v90, v4
	v_mov_b32_e32 v91, v4
	v_mov_b32_e32 v92, v4
	v_mov_b32_e32 v93, v4
	v_mov_b32_e32 v94, v4
	v_mov_b32_e32 v95, v4
	v_mov_b32_e32 v96, v4
	v_mov_b32_e32 v97, v4
	v_mov_b32_e32 v98, v4
	v_mov_b32_e32 v99, v4
	s_waitcnt lgkmcnt(0)
	s_barrier
	s_branch .LBB0_725

; __device__ __forceinline__ void mma_ktile(const bf16_t* cA, const bf16_t* cB, int fo0, int fo1, f32x4 (&acc)[4][4]) {
; #pragma unroll
;   for (int ks = 0; ks < 2; ++ks) {
;     const int fo = ks ? fo1 : fo0;
;     bf16x8 af[4], bfr[4];
; #pragma unroll
;     for (int i = 0; i < 4; ++i) af[i] = *(const bf16x8*)(cA + i * 16 * LDS_STRIDE + fo);
; #pragma unroll
;     for (int j = 0; j < 4; ++j) bfr[j] = *(const bf16x8*)(cB + j * 16 * LDS_STRIDE + fo);
; #pragma unroll
;     for (int i = 0; i < 4; ++i)
; #pragma unroll
;       for (int j = 0; j < 4; ++j)
;         acc[i][j] = __builtin_amdgcn_mfma_f32_16x16x32_bf16(bfr[j], af[i], acc[i][j], 0, 0, 0);
;   }
; }
; __device__ __forceinline__ void phase_gemm_out(const Params& p, char* smem) {
;     ...
;     gemm_core<true>(MG + (size_t)mt * 128 * 1024, 1024, W + (size_t)nt * 128 * 1024, 1024, 1024, acc, smem);
; #pragma unroll
;     for (int i = 0; i < 4; ++i) {
;       const int m = mt * 128 + wm * 64 + i * 16 + (lane & 15);
; #pragma unroll
;       for (int j = 0; j < 4; ++j) {
;         const int n = nt * 128 + wn * 64 + j * 16 + (lane >> 4) * 4;
;         float4* xp = (float4*)(X + (size_t)m * 1024 + n);
;         float4 x = *xp;
;         x.x += acc[i][j][0]; x.y += acc[i][j][1]; x.z += acc[i][j][2]; x.w += acc[i][j][3];
;         *xp = x;
;       }
.LBB0_727:
	v_readlane_b32 s12, v244, 9
	v_readlane_b32 s13, v244, 10
	v_readlane_b32 s14, v244, 0
	v_readlane_b32 s28, v244, 7
	v_readlane_b32 s29, v244, 8
	v_readlane_b32 s0, v243, 48
	v_readlane_b32 s1, v243, 49
	s_load_dword s16, s[12:13], 0x0
	v_and_b32_e32 v0, 15, v178
	v_bfe_u32 v1, v178, 4, 2
	v_lshrrev_b32_e32 v2, 6, v178
	v_lshlrev_b32_e32 v4, 11, v0
	v_lshlrev_b32_e32 v6, 12, v0
	v_readfirstlane_b32 s15, v2
	v_lshl_add_u32 v4, v2, 9, v4
	v_lshl_add_u32 v4, v1, 4, v4
	v_add_u32_e32 v5, 0x8000, v4
	v_lshl_add_u32 v6, v1, 4, v6
	v_and_b32_e32 v7, 63, v178
	v_lshlrev_b32_e32 v7, 4, v7
	s_waitcnt lgkmcnt(0)
.Lg3t_loop:
	s_cmpk_gt_i32 s14, 0x1ff
	s_cbranch_scc1 .Lg3t_done
	s_and_b32 s17, s14, 31
	s_lshr_b32 s18, s14, 5
	s_lshl_b32 s22, s18, 15
	s_add_u32 s22, s22, 0x2000000
	s_add_u32 s24, s28, s22
	s_addc_u32 s25, s29, 0
	s_lshl_b32 s22, s17, 16
	s_add_u32 s26, s0, s22
	s_addc_u32 s27, s1, 0
	s_lshl_b32 s22, s18, 16
	s_lshl_b32 s23, s17, 7
	s_add_u32 s22, s22, s23
	s_add_u32 s22, s22, 0x4000000
	s_add_u32 s22, s10, s22
	s_addc_u32 s23, s11, 0
	global_load_dwordx4 v[112:115], v6, s[22:23]
	global_load_dwordx4 v[116:119], v6, s[22:23] offset:64
	global_load_dwordx4 v[8:11], v4, s[24:25]
	global_load_dwordx4 v[40:43], v4, s[26:27]
	global_load_dwordx4 v[72:75], v5, s[26:27]
	global_load_dwordx4 v[12:15], v4, s[24:25] offset:64
	global_load_dwordx4 v[44:47], v4, s[26:27] offset:64
	global_load_dwordx4 v[76:79], v5, s[26:27] offset:64
	global_load_dwordx4 v[16:19], v4, s[24:25] offset:128
	global_load_dwordx4 v[48:51], v4, s[26:27] offset:128
	global_load_dwordx4 v[80:83], v5, s[26:27] offset:128
	global_load_dwordx4 v[20:23], v4, s[24:25] offset:192
	global_load_dwordx4 v[52:55], v4, s[26:27] offset:192
	global_load_dwordx4 v[84:87], v5, s[26:27] offset:192
	global_load_dwordx4 v[24:27], v4, s[24:25] offset:256
	global_load_dwordx4 v[56:59], v4, s[26:27] offset:256
	global_load_dwordx4 v[88:91], v5, s[26:27] offset:256
	global_load_dwordx4 v[28:31], v4, s[24:25] offset:320
	global_load_dwordx4 v[60:63], v4, s[26:27] offset:320
	global_load_dwordx4 v[92:95], v5, s[26:27] offset:320
	global_load_dwordx4 v[32:35], v4, s[24:25] offset:384
	global_load_dwordx4 v[64:67], v4, s[26:27] offset:384
	global_load_dwordx4 v[96:99], v5, s[26:27] offset:384
	global_load_dwordx4 v[36:39], v4, s[24:25] offset:448
	global_load_dwordx4 v[68:71], v4, s[26:27] offset:448
	global_load_dwordx4 v[100:103], v5, s[26:27] offset:448
	s_barrier
	s_waitcnt vmcnt(21)
	v_mfma_f32_16x16x32_bf16 v[104:107], v[40:43], v[8:11], 0
	v_mfma_f32_16x16x32_bf16 v[108:111], v[72:75], v[8:11], 0
	s_waitcnt vmcnt(18)
	v_mfma_f32_16x16x32_bf16 v[104:107], v[44:47], v[12:15], v[104:107]
	v_mfma_f32_16x16x32_bf16 v[108:111], v[76:79], v[12:15], v[108:111]
	s_waitcnt vmcnt(15)
	v_mfma_f32_16x16x32_bf16 v[104:107], v[48:51], v[16:19], v[104:107]
	v_mfma_f32_16x16x32_bf16 v[108:111], v[80:83], v[16:19], v[108:111]
	s_waitcnt vmcnt(12)
	v_mfma_f32_16x16x32_bf16 v[104:107], v[52:55], v[20:23], v[104:107]
	v_mfma_f32_16x16x32_bf16 v[108:111], v[84:87], v[20:23], v[108:111]
	s_waitcnt vmcnt(9)
	v_mfma_f32_16x16x32_bf16 v[104:107], v[56:59], v[24:27], v[104:107]
	v_mfma_f32_16x16x32_bf16 v[108:111], v[88:91], v[24:27], v[108:111]
	s_waitcnt vmcnt(6)
	v_mfma_f32_16x16x32_bf16 v[104:107], v[60:63], v[28:31], v[104:107]
	v_mfma_f32_16x16x32_bf16 v[108:111], v[92:95], v[28:31], v[108:111]
	s_waitcnt vmcnt(3)
	v_mfma_f32_16x16x32_bf16 v[104:107], v[64:67], v[32:35], v[104:107]
	v_mfma_f32_16x16x32_bf16 v[108:111], v[96:99], v[32:35], v[108:111]
	s_waitcnt vmcnt(0)
	v_mfma_f32_16x16x32_bf16 v[104:107], v[68:71], v[36:39], v[104:107]
	v_mfma_f32_16x16x32_bf16 v[108:111], v[100:103], v[36:39], v[108:111]
	s_nop 15
	s_cmp_eq_u32 s15, 0
	s_cbranch_scc1 .Lg3t_w0
	s_lshl_b32 s12, s15, 11
	v_add_u32_e32 v120, s12, v7
	ds_write_b128 v120, v[104:107]
	ds_write_b128 v120, v[108:111] offset:1024
	s_waitcnt lgkmcnt(0)
	s_barrier
	s_branch .Lg3t_next
.Lg3t_w0:
	s_barrier
	ds_read_b128 v[120:123], v7 offset:2048
	ds_read_b128 v[124:127], v7 offset:3072
	ds_read_b128 v[128:131], v7 offset:4096
	ds_read_b128 v[132:135], v7 offset:5120
	ds_read_b128 v[136:139], v7 offset:6144
	ds_read_b128 v[140:143], v7 offset:7168
	s_waitcnt lgkmcnt(4)
	v_pk_add_f32 v[104:105], v[104:105], v[120:121]
	v_pk_add_f32 v[106:107], v[106:107], v[122:123]
	v_pk_add_f32 v[108:109], v[108:109], v[124:125]
	v_pk_add_f32 v[110:111], v[110:111], v[126:127]
	s_waitcnt lgkmcnt(2)
	v_pk_add_f32 v[104:105], v[104:105], v[128:129]
	v_pk_add_f32 v[106:107], v[106:107], v[130:131]
	v_pk_add_f32 v[108:109], v[108:109], v[132:133]
	v_pk_add_f32 v[110:111], v[110:111], v[134:135]
	s_waitcnt lgkmcnt(0)
	v_pk_add_f32 v[104:105], v[104:105], v[136:137]
	v_pk_add_f32 v[106:107], v[106:107], v[138:139]
	v_pk_add_f32 v[108:109], v[108:109], v[140:141]
	v_pk_add_f32 v[110:111], v[110:111], v[142:143]
	v_pk_add_f32 v[112:113], v[112:113], v[104:105]
	v_pk_add_f32 v[114:115], v[114:115], v[106:107]
	v_pk_add_f32 v[116:117], v[116:117], v[108:109]
	v_pk_add_f32 v[118:119], v[118:119], v[110:111]
	global_store_dwordx4 v6, v[112:115], s[22:23]
	global_store_dwordx4 v6, v[116:119], s[22:23] offset:64
.Lg3t_next:
	s_add_i32 s14, s14, s16
	s_branch .Lg3t_loop
